# w_o / w_down bf16 weight transposes moved from phase 3 into phase 2 (half the workgroups before attention, half after column-max), on top of nt-hinted reads + D2
# baseline (speedup 1.0000x reference)
; #define LAS __attribute__((address_space(3)))
; __device__ __forceinline__ void ph_transpose(const TrJob job, LAS unsigned* scr, int gw, int NGW, int lane) {
;     const float* __restrict__ W = job.W; bf16_t* __restrict__ WT = job.WT; const float* __restrict__ ks = job.kscale;
;     const int ngrp = job.nrows / 64, nitems = (job.K / 64) * ngrp;
;     for (int item = gw; item < nitems; item += NGW) {
;         const int kb = item / ngrp, gq = item % ngrp, k0 = 64 * kb, r0 = 64 * gq, sb = srcbase_of(job.kind, r0);
;         const int n4 = (lane & 15) * 4; const bool inb = sb + n4 < job.N;
; __global__ void __launch_bounds__(512, 2) k_fwd(Args a_unused) {
;     ...
;         j.W = ap->in[12]; j.WT = (bf16_t*)(ws + WS_WO); j.kscale = ap->in[11]; j.K = DM; j.N = DM; j.nrows = DM; j.kind = 0; j.kxor = 2048; j.kscale_n = 2048; ph_transpose(j, scr, gw, NGW, lane);
.LBB0_754:
	s_or_b64 exec, exec, s[6:7]
	s_ashr_i32 s1, s1, 6
	s_lshl_b32 s3, s2, 3
	s_add_i32 s3, s1, s3
	s_lshl_b32 s1, s1, 14
	s_lshl_b32 s34, s74, 3
	s_add_i32 s35, s1, 0
	v_and_b32_e32 v81, 63, v70
	s_cmpk_lt_i32 s3, 0x1000
	s_movk_i32 s4, 0x1000
	s_cselect_b64 s[24:25], -1, 0
	s_cmpk_gt_i32 s3, 0xfff
	v_lshlrev_b32_e32 v89, 2, v81
	v_lshrrev_b32_e32 v83, 3, v81
	v_lshrrev_b32_e32 v1, 4, v81
	v_and_b32_e32 v87, 7, v70
	s_branch .LBB0_839
	s_load_dwordx4 s[8:11], s[22:23], 0x58
	v_and_b32_e32 v71, 60, v89
	v_mov_b32_e32 v2, 0
	v_lshlrev_b32_e32 v4, 2, v71
	v_mov_b32_e32 v5, v2
	s_waitcnt lgkmcnt(0)
	v_lshl_add_u64 v[72:73], s[10:11], 0, v[4:5]
	s_cmp_lg_u64 s[8:9], 0
	v_add_u32_e32 v3, s35, v4
	v_lshlrev_b32_e32 v4, 4, v87
	s_cselect_b64 s[6:7], -1, 0
	v_lshl_add_u64 v[4:5], s[20:21], 0, v[4:5]
	s_mov_b64 s[10:11], 0x4e00000
	s_lshl_b32 s5, s3, 6
	v_lshl_add_u64 v[74:75], v[4:5], 0, s[10:11]
	s_movk_i32 s1, 0x410
	v_mov_b32_e32 v4, s35
	v_or_b32_e32 v5, s5, v83
	v_mad_u32_u24 v91, v87, s1, v4
	v_mul_u32_u24_e32 v4, 0x104, v1
	v_lshlrev_b32_e32 v5, 1, v5
	v_lshlrev_b32_e32 v6, 1, v83
	v_and_b32_e32 v85, 6, v83
	s_sub_i32 s16, 0, s5
	s_lshl_b32 s17, s34, 6
	v_or_b32_e32 v93, 0x70, v5
	s_lshl_b32 s18, s34, 7
	v_lshl_or_b32 v95, s3, 7, v6
	v_or_b32_e32 v97, 0x50, v5
	v_or_b32_e32 v99, 16, v5
	v_or_b32_e32 v101, 48, v5
	s_movk_i32 s19, 0x800
	v_add_u32_e32 v103, v3, v4
	s_movk_i32 s26, 0xffe3
	s_mov_b32 s27, s3
	s_branch .LBB0_757

; #define LAS __attribute__((address_space(3)))
; __device__ __forceinline__ void ph_transpose(const TrJob job, LAS unsigned* scr, int gw, int NGW, int lane) {
;     const float* __restrict__ W = job.W; bf16_t* __restrict__ WT = job.WT; const float* __restrict__ ks = job.kscale;
;     const int ngrp = job.nrows / 64, nitems = (job.K / 64) * ngrp;
;     for (int item = gw; item < nitems; item += NGW) {
;         const int kb = item / ngrp, gq = item % ngrp, k0 = 64 * kb, r0 = 64 * gq, sb = srcbase_of(job.kind, r0);
;         const int n4 = (lane & 15) * 4; const bool inb = sb + n4 < job.N;
; __global__ void __launch_bounds__(512, 2) k_fwd(Args a_unused) {
;     ...
;         j.W = ap->in[17]; j.WT = (bf16_t*)(ws + WS_WDN); j.kscale = nullptr; j.K = DFF; j.N = DM; j.nrows = DM; j.kind = 0; j.kxor = 0; j.kscale_n = 0; ph_transpose(j, scr, gw, NGW, lane);
.LBB0_916:
	s_cmpk_gt_i32 s3, 0x2aff
	s_branch .LBB0_967
	s_load_dwordx2 s[4:5], s[22:23], 0x88
	v_and_b32_e32 v76, 60, v89
	v_mov_b32_e32 v3, 0
	v_lshlrev_b32_e32 v2, 2, v76
	v_add_u32_e32 v4, s35, v2
	s_waitcnt lgkmcnt(0)
	v_lshl_add_u64 v[68:69], s[4:5], 0, v[2:3]
	v_lshlrev_b32_e32 v2, 4, v87
	v_lshl_add_u64 v[2:3], s[20:21], 0, v[2:3]
	s_mov_b64 s[4:5], 0x11a00000
	v_lshl_add_u64 v[70:71], v[2:3], 0, s[4:5]
	s_movk_i32 s1, 0x410
	v_mov_b32_e32 v2, s35
	v_mad_u32_u24 v78, v87, s1, v2
	s_lshl_b32 s1, s3, 6
	v_or_b32_e32 v3, s1, v83
	v_lshlrev_b32_e32 v3, 1, v3
	s_mul_i32 s6, s3, 0xac000
	v_or_b32_e32 v79, 0x70, v3
	v_or_b32_e32 v82, 0x50, v3
	v_or_b32_e32 v84, 16, v3
	v_or_b32_e32 v86, 48, v3
	s_movk_i32 s7, 0x2b00
	v_mov_b32_e32 v3, s6
	v_mul_u32_u24_e32 v2, 0x104, v1
	v_lshlrev_b32_e32 v5, 1, v83
	v_mad_u32_u24 v3, v83, s7, v3
	v_and_b32_e32 v77, 6, v83
	s_sub_i32 s4, 0, s1
	s_lshl_b32 s5, s34, 6
	s_lshl_b32 s10, s34, 7
	v_lshl_or_b32 v80, s3, 7, v5
	v_add_u32_e32 v87, 0x56000, v3
	s_mul_i32 s11, s34, 0xac000
	s_movk_i32 s12, 0x1000
	v_add_u32_e32 v88, v4, v2
	s_movk_i32 s13, 0xffe3
	s_mov_b32 s16, s3
	s_branch .LBB0_919
